# s5 u-tile loads issued together, Mamba dt_bias/a_log prefetched with dt, first grid barrier reads its 16 per-XCD counters in one batch
# speedup vs baseline: 1.0550x; 1.0046x over previous
; #define LAS __attribute__((address_space(3)))
; __device__ __forceinline__ int tidx() { int t = threadIdx.x; asm volatile("" : "+v"(t)); return t; }
; #define LBAR() do { asm volatile("s_waitcnt lgkmcnt(0)" ::: "memory"); __builtin_amdgcn_s_barrier(); asm volatile("" ::: "memory"); } while (0)
; __device__ __forceinline__ void s5_load_u(LAS bf16_t* UB, KP& P_, int bc) {
;     const bf16_t* proj = (const bf16_t*)(p.ws + WS_PROJ);
;     for (int it = 0; it < 4; ++it) { const int item = it * NTHR + tidx(), t = item >> 5, c8 = (item & 31) * 8;
;         *(LAS u32x4*)(UB + t * 264 + c8) = *(const u32x4*)(proj + ((size_t)bc * 64 + t) * NPROJ + C_U + c8); }
; }
; __device__ void s5_a_unit(LAS unsigned char* lds, KP& P_, int l, int bc) {
;     LAS bf16_t* UB = (LAS bf16_t*)lds; LAS bf16_t* XB = (LAS bf16_t*)(lds + 33792);
;     const int tid = tidx(), wid = tid >> 6, lane = tid & 63, fr = lane & 15, fq = lane >> 4;
;     s5_load_u(UB, P_, bc);
;     LBAR();
.LBB0_314:
	s_or_b64 exec, exec, s[6:7]
	v_readlane_b32 s6, v255, 25
	v_readlane_b32 s7, v255, 26
	s_mov_b32 s13, s6
	s_mov_b64 s[24:25], s[30:31]
	s_cmpk_gt_i32 s20, 0x207
	s_mov_b64 s[6:7], -1
	s_cbranch_scc0 .LBB0_340
	s_waitcnt vmcnt(3)
	v_mov_b32_e32 v60, v198
	s_load_dwordx2 s[6:7], s[24:25], 0xe8
	v_mov_b32_e32 v0, v198
	s_add_i32 s22, s20, 0xfffffdf8
	s_lshl_b32 s90, s22, 6
	v_ashrrev_i32_e32 v2, 5, v0
	v_ashrrev_i32_e32 v3, 31, v2
	v_lshl_add_u64 v[8:9], v[2:3], 0, s[90:91]
	s_waitcnt lgkmcnt(0)
	v_mov_b64_e32 v[12:13], s[6:7]
	v_mad_u64_u32 v[10:11], s[14:15], v8, s9, v[12:13]
	v_lshlrev_b32_e32 v0, 4, v0
	v_mad_i32_i24 v11, v9, s9, v11
	v_and_b32_e32 v0, 0x1f0, v0
	v_lshl_add_u64 v[8:9], v[10:11], 0, v[0:1]
	s_movk_i32 s12, 0x1000
	v_add_co_u32_e32 v8, vcc, s12, v8
	s_movk_i32 s23, 0x210
	s_nop 0
	v_addc_co_u32_e32 v9, vcc, 0, v9, vcc
	s_mov_b64 s[14:15], 0x18000
	v_lshl_add_u64 v[20:21], v[8:9], 0, s[14:15]
	v_lshl_add_u64 v[22:23], v[20:21], 0, s[14:15]
	v_lshl_add_u64 v[24:25], v[22:23], 0, s[14:15]
	global_load_dwordx4 v[28:31], v[8:9], off offset:1536
	global_load_dwordx4 v[32:35], v[20:21], off offset:1536
	global_load_dwordx4 v[36:39], v[22:23], off offset:1536
	global_load_dwordx4 v[8:11], v[24:25], off offset:1536
	v_mul_lo_u32 v2, v2, s23
	v_add3_u32 v0, 0, v2, v0
	v_ashrrev_i32_e32 v66, 6, v60
	v_and_b32_e32 v63, 15, v60
	v_and_b32_e32 v88, 63, v60
	s_movk_i32 s26, 0x210
	v_mov_b32_e32 v14, 0
	v_mov_b32_e32 v15, 0
	v_mov_b32_e32 v16, 0
	v_mov_b32_e32 v17, 0
	v_mov_b32_e32 v18, 0
	v_mov_b32_e32 v19, 0
	s_mul_i32 s14, s13, 0x44800
	s_mul_hi_i32 s12, s13, 0x44800
	s_add_u32 s42, s6, s14
	s_addc_u32 s43, s7, s12
	v_cmp_gt_u32_e32 vcc, 32, v88
	v_mov_b32_e32 v12, 0
	v_mov_b32_e32 v13, 0
	s_waitcnt vmcnt(3)
	ds_write_b128 v0, v[28:31]
	s_waitcnt vmcnt(2)
	ds_write_b128 v0, v[32:35] offset:8448
	s_waitcnt vmcnt(1)
	ds_write_b128 v0, v[36:39] offset:16896
	s_waitcnt vmcnt(0)
	ds_write_b128 v0, v[8:11] offset:25344
	v_and_b32_e32 v0, 16, v60
	v_lshl_add_u64 v[2:3], s[42:43], 0, v[0:1]
	v_lshl_add_u64 v[68:69], v[2:3], 0, s[80:81]
	v_lshl_or_b32 v2, v66, 7, v63
	s_waitcnt lgkmcnt(0)
	s_barrier
	v_ashrrev_i32_e32 v3, 31, v2
	v_lshlrev_b64 v[2:3], 5, v[2:3]
	v_lshl_add_u64 v[2:3], v[68:69], 0, v[2:3]
	v_mov_b32_e32 v8, 0
	s_and_saveexec_b64 s[14:15], vcc
	s_cbranch_execz .LBB0_317
	global_load_dwordx4 v[16:19], v[2:3], off
	global_load_dwordx4 v[12:15], v[2:3], off offset:512

; __device__ __forceinline__ void m2_conv_load(KP& P_, int bc, int t, int pcol, u32x4* raw) {
;     const bf16_t* proj = (const bf16_t*)(p.ws + WS_PROJ);
; #pragma unroll
;     for (int tap = 0; tap < 4; ++tap) { const int gr = max(bc * 64 + t - 3 + tap, 0); raw[tap] = *(const u32x4*)(proj + (size_t)gr * NPROJ + pcol); }
; }
; __device__ void m2_c_unit(LAS unsigned char* lds, KP& P_, int l, int bc, int grp) {
;     ...
;     {
;         u32x4 raw[7][4];
;         { int t = tid / 56, cgi = tid - t * 56;
; #pragma unroll
;           for (int it = 0; it < 7; ++it) { m2_conv_load(P_, bc, t, m2_pcol(grp, cgi), raw[it]); t += 9; cgi += 8; if (cgi >= 56) { cgi -= 56; ++t; } } }
.LBB0_340:
	s_and_b64 vcc, exec, s[6:7]
	s_cbranch_vccz .LBB0_305
	v_mov_b32_e32 v2, v198
	s_mov_b32 s12, 0x92492493
	s_load_dwordx2 s[6:7], s[24:25], 0xe8
	s_and_b32 s22, s20, 1
	v_mul_hi_i32 v0, v2, s12
	v_add_u32_e32 v0, v0, v2
	v_lshrrev_b32_e32 v3, 31, v0
	v_ashrrev_i32_e32 v0, 5, v0
	v_add_u32_e32 v147, v0, v3
	s_movk_i32 s12, 0xffc8
	s_lshl_b32 s76, s22, 7
	v_mad_u64_u32 v[120:121], s[14:15], v147, s12, v[2:3]
	s_add_i32 s12, s76, 0x8c0
	s_or_b32 s26, s76, 0x840
	s_mul_i32 s23, s22, 0xc0
	s_add_i32 s42, s23, 0x780
	v_mov_b32_e32 v0, s12
	s_waitcnt vmcnt(15)
	v_mov_b32_e32 v14, s26
	v_cmp_gt_u32_e32 vcc, 40, v120
	s_ashr_i32 s96, s20, 1
	v_mov_b32_e32 v15, s42
	v_cndmask_b32_e32 v3, v0, v14, vcc
	v_cmp_gt_i32_e32 vcc, 24, v120
	s_lshl_b32 s14, s96, 6
	v_lshlrev_b32_e32 v148, 3, v120
	v_cndmask_b32_e32 v3, v3, v15, vcc
	s_add_i32 s15, s14, -3
	v_add_u32_e32 v8, v3, v148
	v_add_u32_e32 v3, s15, v147
	v_ashrrev_i32_e32 v9, 31, v8
	s_waitcnt lgkmcnt(0)
	v_lshl_add_u64 v[8:9], v[8:9], 1, s[6:7]
	v_max_i32_e32 v10, 0, v3
	v_max_i32_e32 v12, -1, v3
	v_max_i32_e32 v3, -2, v3
	v_mad_u64_u32 v[10:11], s[42:43], v10, s9, v[8:9]
	v_add_u32_e32 v12, 1, v12
	v_add_u32_e32 v3, 2, v3
	v_mad_u64_u32 v[12:13], s[42:43], v12, s9, v[8:9]
	global_load_dwordx4 v[116:119], v[10:11], off
	global_load_dwordx4 v[108:111], v[12:13], off
	v_mad_u64_u32 v[10:11], s[42:43], v3, s9, v[8:9]
	v_add_u32_e32 v3, s14, v147
	v_max_i32_e32 v3, 0, v3
	v_cmp_lt_i32_e32 vcc, 47, v120
	v_mad_u64_u32 v[8:9], s[42:43], v3, s9, v[8:9]
	s_nop 0
	v_cndmask_b32_e32 v3, 8, v212, vcc
	v_add_u32_e32 v146, v3, v120
	v_cndmask_b32_e64 v3, 9, 10, vcc
	v_cmp_gt_u32_e32 vcc, 40, v146
	v_add_u32_e32 v144, v3, v147
	v_lshlrev_b32_e32 v145, 3, v146
	v_cndmask_b32_e32 v3, v0, v14, vcc
	v_cmp_gt_i32_e32 vcc, 24, v146
	global_load_dwordx4 v[112:115], v[10:11], off
	global_load_dwordx4 v[104:107], v[8:9], off
	v_cndmask_b32_e32 v3, v3, v15, vcc
	v_add_u32_e32 v8, v3, v145
	v_add_u32_e32 v3, s15, v144
	v_ashrrev_i32_e32 v9, 31, v8
	v_lshl_add_u64 v[8:9], v[8:9], 1, s[6:7]
	v_max_i32_e32 v10, 0, v3
	v_max_i32_e32 v12, -1, v3
	v_max_i32_e32 v3, -2, v3
	v_mad_u64_u32 v[10:11], s[42:43], v10, s9, v[8:9]
	v_add_u32_e32 v12, 1, v12
	v_add_u32_e32 v3, 2, v3
	v_mad_u64_u32 v[12:13], s[42:43], v12, s9, v[8:9]
	global_load_dwordx4 v[100:103], v[10:11], off
	global_load_dwordx4 v[92:95], v[12:13], off
	v_mad_u64_u32 v[10:11], s[42:43], v3, s9, v[8:9]
	v_add_u32_e32 v3, s14, v144
	v_max_i32_e32 v3, 0, v3
	v_cmp_lt_i32_e32 vcc, 47, v146
	v_mad_u64_u32 v[8:9], s[42:43], v3, s9, v[8:9]
	s_nop 0
	v_cndmask_b32_e32 v3, 8, v212, vcc
	v_add_u32_e32 v143, v3, v146
	v_cndmask_b32_e64 v3, 9, 10, vcc
	v_cmp_gt_u32_e32 vcc, 40, v143
	v_add_u32_e32 v141, v3, v144
	v_lshlrev_b32_e32 v142, 3, v143
	v_cndmask_b32_e32 v3, v0, v14, vcc
	v_cmp_gt_i32_e32 vcc, 24, v143
	global_load_dwordx4 v[96:99], v[10:11], off
	global_load_dwordx4 v[88:91], v[8:9], off
	v_cndmask_b32_e32 v3, v3, v15, vcc
	v_add_u32_e32 v8, v3, v142
	v_add_u32_e32 v3, s15, v141
	v_ashrrev_i32_e32 v9, 31, v8
	v_lshl_add_u64 v[8:9], v[8:9], 1, s[6:7]
	v_max_i32_e32 v10, 0, v3
	v_max_i32_e32 v12, -1, v3
	v_max_i32_e32 v3, -2, v3
	v_mad_u64_u32 v[10:11], s[42:43], v10, s9, v[8:9]
	v_add_u32_e32 v12, 1, v12
	v_add_u32_e32 v3, 2, v3
	v_mad_u64_u32 v[12:13], s[42:43], v12, s9, v[8:9]
	global_load_dwordx4 v[84:87], v[10:11], off
	global_load_dwordx4 v[76:79], v[12:13], off
	v_mad_u64_u32 v[10:11], s[42:43], v3, s9, v[8:9]
	v_add_u32_e32 v3, s14, v141
	v_max_i32_e32 v3, 0, v3
	v_cmp_lt_i32_e32 vcc, 47, v143
	v_mad_u64_u32 v[8:9], s[42:43], v3, s9, v[8:9]
	s_nop 0
	v_cndmask_b32_e32 v3, 8, v212, vcc
	v_add_u32_e32 v135, v3, v143
	v_cndmask_b32_e64 v3, 9, 10, vcc
	v_cmp_gt_u32_e32 vcc, 40, v135
	v_add_u32_e32 v133, v3, v141
	v_lshlrev_b32_e32 v134, 3, v135
	v_cndmask_b32_e32 v3, v0, v14, vcc
	v_cmp_gt_i32_e32 vcc, 24, v135
	global_load_dwordx4 v[80:83], v[10:11], off
	global_load_dwordx4 v[72:75], v[8:9], off
	v_cndmask_b32_e32 v3, v3, v15, vcc
	v_add_u32_e32 v8, v3, v134
	v_add_u32_e32 v3, s15, v133
	v_ashrrev_i32_e32 v9, 31, v8
	v_lshl_add_u64 v[8:9], v[8:9], 1, s[6:7]
	v_max_i32_e32 v10, 0, v3
	v_max_i32_e32 v12, -1, v3
	v_max_i32_e32 v3, -2, v3
	v_mad_u64_u32 v[10:11], s[42:43], v10, s9, v[8:9]
	v_add_u32_e32 v12, 1, v12
	v_add_u32_e32 v3, 2, v3
	v_mad_u64_u32 v[12:13], s[42:43], v12, s9, v[8:9]
	global_load_dwordx4 v[68:71], v[10:11], off
	global_load_dwordx4 v[60:63], v[12:13], off
	v_mad_u64_u32 v[10:11], s[42:43], v3, s9, v[8:9]
	v_add_u32_e32 v3, s14, v133
	v_max_i32_e32 v3, 0, v3
	v_cmp_lt_i32_e32 vcc, 47, v135
	v_mad_u64_u32 v[8:9], s[42:43], v3, s9, v[8:9]
	s_nop 0
	v_cndmask_b32_e32 v3, 8, v212, vcc
	v_add_u32_e32 v132, v3, v135
	v_cndmask_b32_e64 v3, 9, 10, vcc
	v_cmp_gt_u32_e32 vcc, 40, v132
	v_add_u32_e32 v130, v3, v133
	v_lshlrev_b32_e32 v131, 3, v132
	v_cndmask_b32_e32 v3, v0, v14, vcc
	v_cmp_gt_i32_e32 vcc, 24, v132
	global_load_dwordx4 v[64:67], v[10:11], off
	global_load_dwordx4 v[56:59], v[8:9], off
	v_cndmask_b32_e32 v3, v3, v15, vcc
	v_add_u32_e32 v8, v3, v131
	v_add_u32_e32 v3, s15, v130
	v_ashrrev_i32_e32 v9, 31, v8
	v_lshl_add_u64 v[8:9], v[8:9], 1, s[6:7]
	v_max_i32_e32 v10, 0, v3
	v_max_i32_e32 v12, -1, v3
	v_max_i32_e32 v3, -2, v3
	v_mad_u64_u32 v[10:11], s[42:43], v10, s9, v[8:9]
	v_add_u32_e32 v12, 1, v12
	v_add_u32_e32 v3, 2, v3
	v_mad_u64_u32 v[12:13], s[42:43], v12, s9, v[8:9]
	global_load_dwordx4 v[52:55], v[10:11], off
	global_load_dwordx4 v[44:47], v[12:13], off
	v_mad_u64_u32 v[10:11], s[42:43], v3, s9, v[8:9]
	v_add_u32_e32 v3, s14, v130
	v_max_i32_e32 v3, 0, v3
	v_cmp_lt_i32_e32 vcc, 47, v132
	v_mad_u64_u32 v[8:9], s[42:43], v3, s9, v[8:9]
; #define LAS __attribute__((address_space(3)))
; __device__ __forceinline__ float softplusf_(float x) { return x > 20.f ? x : log1pf(expf(x)); }
; __device__ __forceinline__ int tidx() { int t = threadIdx.x; asm volatile("" : "+v"(t)); return t; }
; __device__ __forceinline__ void m2_dt(KP& P_, int l, int bc, int grp, LAS float* dtl, LAS float* acs, LAS float* wl, bool write_dec) {
;     const int tid = tidx(), wid = tid >> 6, lane = tid & 63;
;     if (wid < 3) {
;         const int head = grp * 3 + wid; const float draw = ((const float*)(p.ws + WS_DT))[((size_t)bc * 64 + lane) * 8 + head];
;         const float dt = draw < -1e29f ? 0.f : softplusf_(draw + p.in[7][l * 6 + head]);
;         const float a = -expf(p.in[8][l * 6 + head]); float x = dt * a;
; __device__ void m2_c_unit(LAS unsigned char* lds, KP& P_, int l, int bc, int grp) {
;     ...
;           for (int it = 0; it < 7; ++it) { m2_conv_load(P_, bc, t, m2_pcol(grp, cgi), raw[it]); t += 9; cgi += 8; if (cgi >= 56) { cgi -= 56; ++t; } } }
	s_nop 0
	v_cndmask_b32_e32 v3, 8, v212, vcc
	v_add_u32_e32 v129, v3, v132
	v_cndmask_b32_e64 v3, 9, 10, vcc
	v_cmp_gt_u32_e32 vcc, 40, v129
	v_add_u32_e32 v127, v3, v130
	v_lshlrev_b32_e32 v128, 3, v129
	v_cndmask_b32_e32 v3, v0, v14, vcc
	v_cmp_gt_i32_e32 vcc, 24, v129
	global_load_dwordx4 v[48:51], v[10:11], off
	global_load_dwordx4 v[40:43], v[8:9], off
	v_cndmask_b32_e32 v3, v3, v15, vcc
	v_add_u32_e32 v8, v3, v128
	v_add_u32_e32 v3, s15, v127
	v_ashrrev_i32_e32 v9, 31, v8
	v_lshl_add_u64 v[8:9], v[8:9], 1, s[6:7]
	v_max_i32_e32 v10, 0, v3
	v_max_i32_e32 v12, -1, v3
	v_max_i32_e32 v3, -2, v3
	v_mad_u64_u32 v[10:11], s[42:43], v10, s9, v[8:9]
	v_add_u32_e32 v12, 1, v12
	v_add_u32_e32 v3, 2, v3
	v_mad_u64_u32 v[12:13], s[42:43], v12, s9, v[8:9]
	global_load_dwordx4 v[36:39], v[10:11], off
	global_load_dwordx4 v[28:31], v[12:13], off
	v_mad_u64_u32 v[10:11], s[42:43], v3, s9, v[8:9]
	v_add_u32_e32 v3, s14, v127
	v_max_i32_e32 v3, 0, v3
	v_cmp_lt_i32_e32 vcc, 47, v129
	v_mad_u64_u32 v[8:9], s[42:43], v3, s9, v[8:9]
	s_nop 0
	v_cndmask_b32_e32 v3, 8, v212, vcc
	v_add_u32_e32 v126, v3, v129
	v_cndmask_b32_e64 v3, 9, 10, vcc
	v_cmp_gt_u32_e32 vcc, 40, v126
	v_add_u32_e32 v3, v3, v127
	v_lshlrev_b32_e32 v121, 3, v126
	v_cndmask_b32_e32 v0, v0, v14, vcc
	v_cmp_gt_i32_e32 vcc, 24, v126
	global_load_dwordx4 v[32:35], v[10:11], off
	global_load_dwordx4 v[24:27], v[8:9], off
	v_cndmask_b32_e32 v0, v0, v15, vcc
	v_add_u32_e32 v8, v0, v121
	v_add_u32_e32 v0, s15, v3
	v_ashrrev_i32_e32 v9, 31, v8
	v_max_i32_e32 v12, -1, v0
	v_lshl_add_u64 v[8:9], v[8:9], 1, s[6:7]
	v_max_i32_e32 v10, 0, v0
	v_add_u32_e32 v12, 1, v12
	v_max_i32_e32 v0, -2, v0
	v_mad_u64_u32 v[10:11], s[42:43], v10, s9, v[8:9]
	v_mad_u64_u32 v[12:13], s[42:43], v12, s9, v[8:9]
	v_add_u32_e32 v0, 2, v0
	global_load_dwordx4 v[20:23], v[10:11], off
	s_nop 0
	global_load_dwordx4 v[12:15], v[12:13], off
	v_mad_u64_u32 v[10:11], s[42:43], v0, s9, v[8:9]
	v_add_u32_e32 v0, s14, v3
	v_max_i32_e32 v0, 0, v0
	v_mad_u64_u32 v[8:9], s[14:15], v0, s9, v[8:9]
	global_load_dwordx4 v[16:19], v[10:11], off
	s_nop 0
	global_load_dwordx4 v[8:11], v[8:9], off
	v_cmp_lt_u32_e64 s[14:15], 39, v126
	v_mov_b32_e32 v149, v198
	v_cmp_lt_i32_e64 s[68:69], 23, v120
	v_writelane_b32 v255, s14, 32
	v_ashrrev_i32_e32 v0, 6, v149
	v_cmp_lt_u32_e64 s[66:67], 39, v120
	v_cmp_lt_i32_e64 s[64:65], 23, v146
	v_cmp_lt_u32_e64 s[62:63], 39, v146
	v_cmp_lt_i32_e64 s[60:61], 23, v143
	v_cmp_lt_u32_e64 s[58:59], 39, v143
	v_cmp_lt_i32_e64 s[56:57], 23, v135
	v_cmp_lt_u32_e64 s[54:55], 39, v135
	v_cmp_lt_i32_e64 s[52:53], 23, v132
	v_cmp_lt_u32_e64 s[50:51], 39, v132
	v_cmp_lt_i32_e64 s[48:49], 23, v129
	v_cmp_lt_u32_e64 s[46:47], 39, v129
	v_cmp_lt_i32_e64 s[44:45], 23, v126
	v_writelane_b32 v255, s15, 33
	v_cmp_gt_i32_e32 vcc, 3, v0
	s_and_saveexec_b64 s[70:71], vcc
	s_cbranch_execz .LBB0_349
	v_mad_u64_u32 v[124:125], s[14:15], s22, 3, v[0:1]
	s_load_dwordx2 s[42:43], s[24:25], 0x38
	s_load_dwordx2 s[78:79], s[24:25], 0x40
	v_mad_u64_u32 v[160:161], s[14:15], s13, 6, v[124:125]
	v_ashrrev_i32_e32 v161, 31, v160
	s_waitcnt lgkmcnt(0)
	v_lshl_add_u64 v[162:163], v[160:161], 2, s[42:43]
	v_lshl_add_u64 v[164:165], v[160:161], 2, s[78:79]
	global_load_dword v166, v[162:163], off
	global_load_dword v167, v[164:165], off
	s_ashr_i32 s97, s96, 31
	s_lshl_b64 s[14:15], s[96:97], 11
	v_and_b32_e32 v150, 63, v149
	s_add_u32 s14, s6, s14
	s_addc_u32 s15, s7, s15
	v_lshlrev_b32_e32 v0, 5, v150
	v_ashrrev_i32_e32 v125, 31, v124
	v_lshl_add_u64 v[122:123], s[14:15], 0, v[0:1]
	v_lshl_add_u64 v[122:123], v[124:125], 2, v[122:123]
	v_add_co_u32_e32 v122, vcc, 0xe9fb000, v122
	s_mov_b32 s12, 0xefa18f08
	s_nop 0
	v_addc_co_u32_e32 v123, vcc, 0, v123, vcc
	global_load_dword v125, v[122:123], off offset:2048
	s_waitcnt vmcnt(0)
	v_cmp_ngt_f32_e32 vcc, s12, v125
	s_and_saveexec_b64 s[14:15], vcc
	s_xor_b64 s[72:73], exec, s[14:15]
	s_cbranch_execz .LBB0_346
	s_load_dwordx2 s[14:15], s[24:25], 0x38
	v_mad_u64_u32 v[122:123], s[42:43], s13, 6, v[124:125]
	v_ashrrev_i32_e32 v123, 31, v122
	s_mov_b32 s12, 0x41a00000
	s_waitcnt lgkmcnt(0)
	v_lshl_add_u64 v[152:153], v[122:123], 2, s[14:15]
	v_mov_b32_e32 v0, v166
	s_waitcnt vmcnt(0)
	v_add_f32_e32 v0, v125, v0
	v_cmp_nlt_f32_e32 vcc, s12, v0
	s_and_saveexec_b64 s[74:75], vcc
	s_cbranch_execz .LBB0_345
; __device__ __forceinline__ float softplusf_(float x) { return x > 20.f ? x : log1pf(expf(x)); }
; __device__ __forceinline__ void m2_dt(KP& P_, int l, int bc, int grp, LAS float* dtl, LAS float* acs, LAS float* wl, bool write_dec) {
;     ...
;         const float dt = draw < -1e29f ? 0.f : softplusf_(draw + p.in[7][l * 6 + head]);
	v_mul_f32_e32 v124, 0x3fb8aa3b, v0
	v_rndne_f32_e32 v125, v124
	v_sub_f32_e32 v151, v124, v125
	v_fma_f32 v124, v0, s17, -v124
	v_fmac_f32_e32 v124, 0x32a5705f, v0
	v_add_f32_e32 v124, v151, v124
	v_cvt_i32_f32_e32 v125, v125
	v_exp_f32_e32 v124, v124
	v_cmp_ngt_f32_e32 vcc, s93, v0
	s_mov_b32 s12, 0x3f2aaaab
	v_ldexp_f32 v124, v124, v125
	v_cndmask_b32_e32 v124, 0, v124, vcc
	v_cmp_nlt_f32_e32 vcc, s5, v0
	s_nop 1
	v_cndmask_b32_e32 v0, v213, v124, vcc
	v_add_f32_e32 v151, 1.0, v0
	v_add_f32_e32 v124, -1.0, v151
	v_sub_f32_e32 v125, v124, v151
	v_add_f32_e32 v125, 1.0, v125
	v_sub_f32_e32 v124, v0, v124
	v_add_f32_e32 v152, v124, v125
	v_frexp_mant_f32_e32 v153, v151
	v_cvt_f64_f32_e32 v[124:125], v151
	v_frexp_exp_i32_f64_e32 v124, v[124:125]
	v_cmp_gt_f32_e32 vcc, s12, v153
	s_mov_b32 s12, 0x3f317218
	s_nop 0
	v_subbrev_co_u32_e32 v158, vcc, 0, v124, vcc
	v_sub_u32_e32 v124, 0, v158
	v_ldexp_f32 v125, v151, v124
	v_add_f32_e32 v151, -1.0, v125
	v_add_f32_e32 v153, 1.0, v125
	v_ldexp_f32 v124, v152, v124
	v_add_f32_e32 v152, 1.0, v151
	v_add_f32_e32 v154, -1.0, v153
	v_sub_f32_e32 v152, v125, v152
	v_sub_f32_e32 v125, v125, v154
	v_add_f32_e32 v152, v124, v152
	v_add_f32_e32 v124, v124, v125
	v_add_f32_e32 v159, v153, v124
	v_rcp_f32_e32 v161, v159
	v_sub_f32_e32 v125, v153, v159
	v_add_f32_e32 v160, v124, v125
	v_add_f32_e32 v125, v151, v152
	v_sub_f32_e32 v124, v151, v125
	v_mul_f32_e32 v162, v125, v161
	v_add_f32_e32 v151, v152, v124
	v_mul_f32_e32 v152, v159, v162
	v_fma_f32 v154, v162, v159, -v152
	v_fmac_f32_e32 v154, v162, v160
	v_add_f32_e32 v124, v152, v154
	v_sub_f32_e32 v153, v125, v124
	v_pk_add_f32 v[156:157], v[124:125], v[152:153] neg_lo:[0,1] neg_hi:[0,1]
	v_mov_b32_e32 v155, v124
	v_pk_add_f32 v[124:125], v[156:157], v[154:155] neg_lo:[0,1] neg_hi:[0,1]
	s_nop 0
	v_add_f32_e32 v125, v151, v125
	v_add_f32_e32 v124, v124, v125
	v_add_f32_e32 v125, v153, v124
	v_mul_f32_e32 v151, v161, v125
	v_mul_f32_e32 v152, v159, v151
	v_fma_f32 v154, v151, v159, -v152
	v_fmac_f32_e32 v154, v151, v160
	v_sub_f32_e32 v153, v153, v125
	v_add_f32_e32 v159, v124, v153
	v_add_f32_e32 v124, v152, v154
	v_sub_f32_e32 v153, v125, v124
	v_pk_add_f32 v[156:157], v[124:125], v[152:153] neg_lo:[0,1] neg_hi:[0,1]
	v_mov_b32_e32 v155, v124
	v_pk_add_f32 v[124:125], v[156:157], v[154:155] neg_lo:[0,1] neg_hi:[0,1]
	s_nop 0
	v_add_f32_e32 v125, v159, v125
	v_add_f32_e32 v124, v124, v125
	v_add_f32_e32 v125, v162, v151
	v_add_f32_e32 v124, v153, v124
	v_sub_f32_e32 v152, v125, v162
	v_mul_f32_e32 v124, v161, v124
	v_sub_f32_e32 v151, v151, v152
	v_add_f32_e32 v151, v151, v124
	v_add_f32_e32 v152, v125, v151
	v_mul_f32_e32 v154, v152, v152
	v_mov_b32_e32 v124, 0x3ecc95a3
	v_fmamk_f32 v124, v154, 0x3e9b6dac, v124
	v_fmaak_f32 v179, v154, v124, 0x3f2aaada
	v_cvt_f32_i32_e32 v124, v158
	v_sub_f32_e32 v125, v152, v125
	v_sub_f32_e32 v125, v151, v125
	v_ldexp_f32 v151, v125, 1
	v_mul_f32_e32 v125, v152, v154
	v_pk_mul_f32 v[154:155], v[124:125], v[178:179]
	v_ldexp_f32 v153, v152, 1
	v_fma_f32 v152, v124, s12, -v154
	v_fmac_f32_e32 v152, 0xb102e308, v124
	v_pk_add_f32 v[124:125], v[154:155], v[152:153]
	v_mov_b32_e32 v156, v154
	v_sub_f32_e32 v153, v125, v153
	v_sub_f32_e32 v153, v155, v153
	v_add_f32_e32 v157, v151, v153
	v_pk_add_f32 v[154:155], v[124:125], v[154:155] neg_lo:[0,1] neg_hi:[0,1]
	v_pk_add_f32 v[158:159], v[124:125], v[156:157]
	v_mov_b32_e32 v153, v124
	v_mov_b32_e32 v155, v159
	v_pk_add_f32 v[160:161], v[152:153], v[154:155] neg_lo:[0,1] neg_hi:[0,1]
	v_pk_add_f32 v[152:153], v[152:153], v[154:155]
	v_mov_b32_e32 v156, v157
	v_pk_add_f32 v[154:155], v[152:153], v[124:125] op_sel:[1,0] op_sel_hi:[0,1] neg_lo:[0,1] neg_hi:[0,1]
	v_pk_add_f32 v[162:163], v[158:159], v[154:155] op_sel_hi:[1,0] neg_lo:[0,1] neg_hi:[0,1]
	v_mov_b32_e32 v158, v159
	v_mov_b32_e32 v159, v153
	v_pk_mov_b32 v[154:155], v[124:125], v[154:155] op_sel:[1,0]
	v_mov_b32_e32 v157, v124
	v_pk_add_f32 v[154:155], v[158:159], v[154:155] neg_lo:[0,1] neg_hi:[0,1]
	v_mov_b32_e32 v162, v160
	v_pk_add_f32 v[124:125], v[156:157], v[154:155] neg_lo:[0,1] neg_hi:[0,1]
	v_mov_b32_e32 v161, v153
	v_pk_add_f32 v[154:155], v[162:163], v[124:125]
	s_mov_b32 s12, 0x7f800000
	v_pk_add_f32 v[156:157], v[154:155], v[154:155] op_sel:[0,1] op_sel_hi:[1,0]
	v_cmp_neq_f32_e32 vcc, s12, v0
	v_pk_add_f32 v[152:153], v[152:153], v[156:157] op_sel:[1,0] op_sel_hi:[0,1]
	v_mov_b32_e32 v155, v152
	v_pk_add_f32 v[158:159], v[154:155], v[160:161] neg_lo:[0,1] neg_hi:[0,1]
	v_mov_b32_e32 v125, v156
	v_sub_f32_e32 v151, v154, v158
	v_pk_add_f32 v[124:125], v[124:125], v[158:159] neg_lo:[0,1] neg_hi:[0,1]
	v_sub_f32_e32 v151, v160, v151
	v_add_f32_e32 v124, v124, v151
	v_add_f32_e32 v124, v124, v125
	v_add_f32_e32 v124, v152, v124
	s_mov_b32 s12, 0x33800000
	v_cndmask_b32_e32 v124, v213, v124, vcc
	v_cmp_lt_f32_e64 vcc, |v0|, s12
	s_nop 1
	v_cndmask_b32_e32 v0, v124, v0, vcc

; __device__ __forceinline__ float softplusf_(float x) { return x > 20.f ? x : log1pf(expf(x)); }
; __device__ __forceinline__ void m2_dt(KP& P_, int l, int bc, int grp, LAS float* dtl, LAS float* acs, LAS float* wl, bool write_dec) {
;     ...
;         const float dt = draw < -1e29f ? 0.f : softplusf_(draw + p.in[7][l * 6 + head]);
;         const float a = -expf(p.in[8][l * 6 + head]); float x = dt * a;
; #pragma unroll
;         for (int off = 1; off < 64; off <<= 1) { const float v = __shfl_up(x, off); if (lane >= off) x += v; }
;         const float tot = __shfl(x, 63);
;         dtl[wid * 64 + lane] = dt; acs[wid * 64 + lane] = x; wl[wid * 64 + lane] = dt * __expf(tot - x);
.LBB0_346:
	s_andn2_saveexec_b64 s[14:15], s[72:73]
	v_mad_u64_u32 v[122:123], s[42:43], s13, 6, v[124:125]
	v_ashrrev_i32_e32 v123, 31, v122
	v_mov_b32_e32 v0, 0
	s_or_b64 exec, exec, s[14:15]
	s_load_dwordx2 s[14:15], s[24:25], 0x40
	s_waitcnt lgkmcnt(0)
	v_lshl_add_u64 v[122:123], v[122:123], 2, s[14:15]
	v_mov_b32_e32 v122, v167
	s_waitcnt vmcnt(0)
	v_mul_f32_e32 v123, 0x3fb8aa3b, v122
	v_fma_f32 v124, v122, s17, -v123
	v_rndne_f32_e32 v125, v123
	v_fmac_f32_e32 v124, 0x32a5705f, v122
	v_sub_f32_e32 v123, v123, v125
	v_add_f32_e32 v123, v123, v124
	v_exp_f32_e32 v123, v123
	v_cvt_i32_f32_e32 v124, v125
	v_cmp_ngt_f32_e32 vcc, s93, v122
	v_ldexp_f32 v123, v123, v124
	s_nop 0
	v_cndmask_b32_e32 v123, 0, v123, vcc
	v_cmp_nlt_f32_e32 vcc, s5, v122
	v_add_u32_e32 v124, -1, v204
	s_nop 0
	v_cndmask_b32_e32 v122, v213, v123, vcc
	v_cmp_lt_i32_e32 vcc, v124, v205
	v_mul_f32_e64 v123, v0, -v122
	s_nop 0
	v_cndmask_b32_e32 v124, v124, v204, vcc
	v_lshlrev_b32_e32 v124, 2, v124
	ds_bpermute_b32 v124, v124, v123
	v_cmp_eq_u32_e32 vcc, 0, v150
	s_waitcnt lgkmcnt(0)
	v_fma_f32 v122, v0, -v122, v124
	v_cndmask_b32_e32 v122, v122, v123, vcc
	v_add_u32_e32 v123, -2, v204
	v_cmp_lt_i32_e32 vcc, v123, v205
	v_lshl_add_u32 v124, v149, 2, 0
	v_add_u32_e32 v125, 0x16000, v124
	v_cndmask_b32_e32 v123, v123, v204, vcc
	v_lshlrev_b32_e32 v123, 2, v123
	ds_bpermute_b32 v123, v123, v122
	v_cmp_gt_u32_e32 vcc, 2, v150
	ds_write_b32 v125, v0
	v_add_u32_e32 v125, 0x16300, v124
	s_waitcnt lgkmcnt(1)
	v_add_f32_e32 v123, v122, v123
	v_cndmask_b32_e32 v122, v123, v122, vcc
	v_add_u32_e32 v123, -4, v204
	v_cmp_lt_i32_e32 vcc, v123, v205
	s_nop 1
	v_cndmask_b32_e32 v123, v123, v204, vcc
	v_lshlrev_b32_e32 v123, 2, v123
	ds_bpermute_b32 v123, v123, v122
	v_cmp_gt_u32_e32 vcc, 4, v150
	s_waitcnt lgkmcnt(0)
	v_add_f32_e32 v123, v122, v123
	v_cndmask_b32_e32 v122, v123, v122, vcc
	v_add_u32_e32 v123, -8, v204
	v_cmp_lt_i32_e32 vcc, v123, v205
	s_nop 1
	v_cndmask_b32_e32 v123, v123, v204, vcc
	v_lshlrev_b32_e32 v123, 2, v123
	ds_bpermute_b32 v123, v123, v122
	v_cmp_gt_u32_e32 vcc, 8, v150
	s_waitcnt lgkmcnt(0)
	v_add_f32_e32 v123, v122, v123
	v_cndmask_b32_e32 v122, v123, v122, vcc
	v_add_u32_e32 v123, -16, v204
	v_cmp_lt_i32_e32 vcc, v123, v205
	s_nop 1
	v_cndmask_b32_e32 v123, v123, v204, vcc
	v_lshlrev_b32_e32 v123, 2, v123
	ds_bpermute_b32 v123, v123, v122
	v_cmp_gt_u32_e32 vcc, 16, v150
	s_waitcnt lgkmcnt(0)
	v_add_f32_e32 v123, v122, v123
	v_cndmask_b32_e32 v122, v123, v122, vcc
	v_subrev_u32_e32 v123, 32, v204
	v_cmp_lt_i32_e32 vcc, v123, v205
	s_nop 1
	v_cndmask_b32_e32 v123, v123, v204, vcc
	v_lshlrev_b32_e32 v123, 2, v123
	ds_bpermute_b32 v123, v123, v122
	v_cmp_gt_u32_e32 vcc, 32, v150
	s_waitcnt lgkmcnt(0)
	v_add_f32_e32 v123, v122, v123
	v_cndmask_b32_e32 v122, v123, v122, vcc
	v_lshl_or_b32 v123, v204, 2, v214
	ds_bpermute_b32 v123, v123, v122
	ds_write_b32 v125, v122
	s_waitcnt lgkmcnt(1)
	v_sub_f32_e32 v122, v123, v122
	v_mul_f32_e32 v122, 0x3fb8aa3b, v122
	v_exp_f32_e32 v122, v122
	s_nop 0
	v_mul_f32_e32 v0, v0, v122
	v_add_u32_e32 v122, 0x16600, v124
	ds_write_b32 v122, v0

; #define LAS __attribute__((address_space(3)))
; __device__ __forceinline__ int tidx() { int t = threadIdx.x; asm volatile("" : "+v"(t)); return t; }
; #define LBAR() do { asm volatile("s_waitcnt lgkmcnt(0)" ::: "memory"); __builtin_amdgcn_s_barrier(); asm volatile("" ::: "memory"); } while (0)
; __device__ __forceinline__ void s5_load_u(LAS bf16_t* UB, KP& P_, int bc) {
;     const bf16_t* proj = (const bf16_t*)(p.ws + WS_PROJ);
;     for (int it = 0; it < 4; ++it) { const int item = it * NTHR + tidx(), t = item >> 5, c8 = (item & 31) * 8;
;         *(LAS u32x4*)(UB + t * 264 + c8) = *(const u32x4*)(proj + ((size_t)bc * 64 + t) * NPROJ + C_U + c8); }
; }
; __device__ void s5_a_unit(LAS unsigned char* lds, KP& P_, int l, int bc) {
;     LAS bf16_t* UB = (LAS bf16_t*)lds; LAS bf16_t* XB = (LAS bf16_t*)(lds + 33792);
;     const int tid = tidx(), wid = tid >> 6, lane = tid & 63, fr = lane & 15, fq = lane >> 4;
;     s5_load_u(UB, P_, bc);
;     LBAR();
.LBB0_614:
	s_or_b64 exec, exec, s[14:15]
	v_readlane_b32 s14, v255, 25
	v_readlane_b32 s15, v255, 26
	s_mov_b32 s58, s14
	s_mov_b64 s[20:21], s[30:31]
	s_cmpk_gt_i32 s13, 0x207
	s_mov_b64 s[14:15], -1
	s_cbranch_scc0 .LBB0_634
	s_waitcnt vmcnt(15)
	v_mov_b32_e32 v14, v198
	s_load_dwordx2 s[24:25], s[20:21], 0xe8
	v_mov_b32_e32 v0, v198
	s_add_i32 s15, s13, 0xfffffdf8
	s_lshl_b32 s90, s15, 6
	v_ashrrev_i32_e32 v2, 5, v0
	v_ashrrev_i32_e32 v3, 31, v2
	v_lshl_add_u64 v[8:9], v[2:3], 0, s[90:91]
	s_waitcnt lgkmcnt(0)
	v_mov_b64_e32 v[12:13], s[24:25]
	v_mad_u64_u32 v[10:11], s[22:23], v8, s9, v[12:13]
	v_lshlrev_b32_e32 v0, 4, v0
	v_mad_i32_i24 v11, v9, s9, v11
	v_and_b32_e32 v0, 0x1f0, v0
	v_lshl_add_u64 v[8:9], v[10:11], 0, v[0:1]
	s_movk_i32 s12, 0x1000
	v_add_co_u32_e32 v8, vcc, s12, v8
	s_movk_i32 s26, 0x210
	s_nop 0
	v_addc_co_u32_e32 v9, vcc, 0, v9, vcc
	s_mov_b64 s[22:23], 0x18000
	v_lshl_add_u64 v[20:21], v[8:9], 0, s[22:23]
	v_lshl_add_u64 v[22:23], v[20:21], 0, s[22:23]
	v_lshl_add_u64 v[24:25], v[22:23], 0, s[22:23]
	global_load_dwordx4 v[28:31], v[8:9], off offset:1536
	global_load_dwordx4 v[32:35], v[20:21], off offset:1536
	global_load_dwordx4 v[36:39], v[22:23], off offset:1536
	global_load_dwordx4 v[8:11], v[24:25], off offset:1536
	v_mul_lo_u32 v2, v2, s26
	v_add3_u32 v0, 0, v2, v0
	v_ashrrev_i32_e32 v103, 6, v14
	v_and_b32_e32 v104, 63, v14
	v_and_b32_e32 v105, 15, v14
	s_mov_b32 s14, 0
	v_cmp_gt_u32_e64 s[42:43], 32, v104
	s_movk_i32 s12, 0x1100
	s_mul_i32 s22, s58, 0x44800
	s_add_u32 s22, s24, s22
	v_lshlrev_b32_e32 v13, 2, v104
	s_waitcnt vmcnt(3)
	ds_write_b128 v0, v[28:31]
	s_waitcnt vmcnt(2)
	ds_write_b128 v0, v[32:35] offset:8448
	s_waitcnt vmcnt(1)
	ds_write_b128 v0, v[36:39] offset:16896
	s_waitcnt vmcnt(0)
	ds_write_b128 v0, v[8:11] offset:25344
	v_mul_lo_u32 v0, v103, s12
	v_add_u32_e32 v10, 0, v0
	s_mul_hi_i32 s12, s58, 0x44800
	v_lshrrev_b32_e32 v0, 1, v14
	s_addc_u32 s23, s25, s12
	v_and_b32_e32 v11, 24, v0
	v_and_b32_e32 v0, 16, v14
	v_lshl_add_u64 v[2:3], s[22:23], 0, v[0:1]
	v_and_b32_e32 v0, 48, v14
	s_waitcnt lgkmcnt(0)
	s_barrier
	s_movk_i32 s12, 0x110
	v_add_u32_e32 v106, 0, v0
	v_lshlrev_b32_e32 v0, 3, v104
	s_add_u32 s22, s22, 0xef05000
	v_mad_u32_u24 v12, v105, s12, v10
	v_lshl_add_u64 v[8:9], s[24:25], 0, v[0:1]
	s_mov_b64 s[24:25], 0xe790000
	v_lshl_add_u64 v[2:3], v[2:3], 0, s[80:81]
	s_addc_u32 s23, s23, 0
	s_lshl_b32 s90, s15, 4
	v_lshl_add_u64 v[46:47], v[8:9], 0, s[24:25]
	v_mul_u32_u24_e32 v0, 0x210, v105
	s_mov_b64 s[24:25], -1
	v_add_u32_e32 v107, v12, v11
	v_add_u32_e32 v108, v10, v13
	s_branch .LBB0_617

; __device__ __forceinline__ void m2_conv_load(KP& P_, int bc, int t, int pcol, u32x4* raw) {
;     const bf16_t* proj = (const bf16_t*)(p.ws + WS_PROJ);
; #pragma unroll
;     for (int tap = 0; tap < 4; ++tap) { const int gr = max(bc * 64 + t - 3 + tap, 0); raw[tap] = *(const u32x4*)(proj + (size_t)gr * NPROJ + pcol); }
; }
; __device__ void m2_a_unit(LAS unsigned char* lds, KP& P_, int l, int bc, int grp) {
;     ...
;     { int t = tid / 40, cgi = tid - t * 40;
; #pragma unroll
;       for (int it = 0; it < 5; ++it) { m2_conv_load(P_, bc, t, m2_pcol(grp, cgi), raw[it]); t += 12; cgi += 32; if (cgi >= 40) { cgi -= 40; ++t; } } }
.LBB0_634:
	s_and_b64 vcc, exec, s[14:15]
	s_cbranch_vccz .LBB0_605
	v_mov_b32_e32 v2, v198
	s_mov_b32 s12, 0x66666667
	s_and_b32 s63, s13, 1
	v_mul_hi_i32 v0, v2, s12
	v_lshrrev_b32_e32 v3, 31, v0
	v_ashrrev_i32_e32 v0, 4, v0
	v_add_u32_e32 v109, v0, v3
	s_movk_i32 s12, 0xffd8
	v_mad_u64_u32 v[88:89], s[14:15], v109, s12, v[2:3]
	s_lshl_b32 s59, s63, 7
	s_add_i32 s14, s59, 0x8c0
	s_or_b32 s15, s59, 0x840
	s_mul_i32 s64, s63, 0xc0
	s_load_dwordx2 s[24:25], s[20:21], 0xe8
	s_add_i32 s26, s64, 0x780
	v_mov_b32_e32 v0, s14
	s_waitcnt vmcnt(15)
	v_mov_b32_e32 v14, s15
	v_cmp_gt_u32_e32 vcc, 40, v88
	s_ashr_i32 s22, s13, 1
	v_mov_b32_e32 v15, s26
	v_cndmask_b32_e32 v3, v0, v14, vcc
	v_cmp_gt_i32_e32 vcc, 24, v88
	s_lshl_b32 s12, s22, 6
	v_lshlrev_b32_e32 v110, 3, v88
	v_cndmask_b32_e32 v3, v3, v15, vcc
	s_add_i32 s23, s12, -3
	v_add_u32_e32 v8, v3, v110
	v_add_u32_e32 v3, s23, v109
	v_ashrrev_i32_e32 v9, 31, v8
	s_waitcnt lgkmcnt(0)
	v_lshl_add_u64 v[8:9], v[8:9], 1, s[24:25]
	v_max_i32_e32 v10, 0, v3
	v_max_i32_e32 v12, -1, v3
	v_max_i32_e32 v3, -2, v3
	v_mad_u64_u32 v[10:11], s[14:15], v10, s9, v[8:9]
	v_add_u32_e32 v12, 1, v12
	v_add_u32_e32 v3, 2, v3
	v_mad_u64_u32 v[12:13], s[14:15], v12, s9, v[8:9]
	global_load_dwordx4 v[84:87], v[10:11], off
	global_load_dwordx4 v[76:79], v[12:13], off
	v_mad_u64_u32 v[10:11], s[14:15], v3, s9, v[8:9]
	v_add_u32_e32 v3, s12, v109
	v_max_i32_e32 v3, 0, v3
	v_cmp_lt_i32_e32 vcc, 7, v88
	v_mad_u64_u32 v[8:9], s[14:15], v3, s9, v[8:9]
	s_nop 0
	v_cndmask_b32_e64 v3, 32, -8, vcc
	v_add_u32_e32 v108, v3, v88
	v_cndmask_b32_e64 v3, 12, 13, vcc
	v_cmp_gt_u32_e32 vcc, 40, v108
	v_add_u32_e32 v106, v3, v109
	v_lshlrev_b32_e32 v107, 3, v108
	v_cndmask_b32_e32 v3, v0, v14, vcc
	v_cmp_gt_i32_e32 vcc, 24, v108
	global_load_dwordx4 v[80:83], v[10:11], off
	global_load_dwordx4 v[72:75], v[8:9], off
	v_cndmask_b32_e32 v3, v3, v15, vcc
	v_add_u32_e32 v8, v3, v107
	v_add_u32_e32 v3, s23, v106
	v_ashrrev_i32_e32 v9, 31, v8
	v_lshl_add_u64 v[8:9], v[8:9], 1, s[24:25]
	v_max_i32_e32 v10, 0, v3
	v_max_i32_e32 v12, -1, v3
	v_max_i32_e32 v3, -2, v3
	v_mad_u64_u32 v[10:11], s[14:15], v10, s9, v[8:9]
	v_add_u32_e32 v12, 1, v12
	v_add_u32_e32 v3, 2, v3
	v_mad_u64_u32 v[12:13], s[14:15], v12, s9, v[8:9]
	global_load_dwordx4 v[68:71], v[10:11], off
	global_load_dwordx4 v[60:63], v[12:13], off
	v_mad_u64_u32 v[10:11], s[14:15], v3, s9, v[8:9]
	v_add_u32_e32 v3, s12, v106
	v_max_i32_e32 v3, 0, v3
	v_cmp_lt_i32_e32 vcc, 7, v108
	v_mad_u64_u32 v[8:9], s[14:15], v3, s9, v[8:9]
	s_nop 0
	v_cndmask_b32_e64 v3, 32, -8, vcc
	v_add_u32_e32 v105, v3, v108
	v_cndmask_b32_e64 v3, 12, 13, vcc
	v_cmp_gt_u32_e32 vcc, 40, v105
	v_add_u32_e32 v103, v3, v106
	v_lshlrev_b32_e32 v104, 3, v105
	v_cndmask_b32_e32 v3, v0, v14, vcc
	v_cmp_gt_i32_e32 vcc, 24, v105
	global_load_dwordx4 v[64:67], v[10:11], off
	global_load_dwordx4 v[56:59], v[8:9], off
	v_cndmask_b32_e32 v3, v3, v15, vcc
	v_add_u32_e32 v8, v3, v104
	v_add_u32_e32 v3, s23, v103
	v_ashrrev_i32_e32 v9, 31, v8
	v_lshl_add_u64 v[8:9], v[8:9], 1, s[24:25]
	v_max_i32_e32 v10, 0, v3
	v_max_i32_e32 v12, -1, v3
	v_max_i32_e32 v3, -2, v3
	v_mad_u64_u32 v[10:11], s[14:15], v10, s9, v[8:9]
	v_add_u32_e32 v12, 1, v12
	v_add_u32_e32 v3, 2, v3
	v_mad_u64_u32 v[12:13], s[14:15], v12, s9, v[8:9]
	global_load_dwordx4 v[52:55], v[10:11], off
	global_load_dwordx4 v[44:47], v[12:13], off
	v_mad_u64_u32 v[10:11], s[14:15], v3, s9, v[8:9]
	v_add_u32_e32 v3, s12, v103
	v_max_i32_e32 v3, 0, v3
	v_cmp_lt_i32_e32 vcc, 7, v105
	v_mad_u64_u32 v[8:9], s[14:15], v3, s9, v[8:9]
	s_nop 0
	v_cndmask_b32_e64 v3, 32, -8, vcc
	v_add_u32_e32 v97, v3, v105
	v_cndmask_b32_e64 v3, 12, 13, vcc
	v_cmp_gt_u32_e32 vcc, 40, v97
	v_add_u32_e32 v95, v3, v103
	v_lshlrev_b32_e32 v96, 3, v97
	v_cndmask_b32_e32 v3, v0, v14, vcc
	v_cmp_gt_i32_e32 vcc, 24, v97
	global_load_dwordx4 v[48:51], v[10:11], off
	global_load_dwordx4 v[40:43], v[8:9], off
	v_cndmask_b32_e32 v3, v3, v15, vcc
	v_add_u32_e32 v8, v3, v96
	v_add_u32_e32 v3, s23, v95
	v_ashrrev_i32_e32 v9, 31, v8
	v_lshl_add_u64 v[8:9], v[8:9], 1, s[24:25]
	v_max_i32_e32 v10, 0, v3
	v_max_i32_e32 v12, -1, v3
	v_max_i32_e32 v3, -2, v3
	v_mad_u64_u32 v[10:11], s[14:15], v10, s9, v[8:9]
	v_add_u32_e32 v12, 1, v12
	v_add_u32_e32 v3, 2, v3
	v_mad_u64_u32 v[12:13], s[14:15], v12, s9, v[8:9]
	global_load_dwordx4 v[36:39], v[10:11], off
	global_load_dwordx4 v[28:31], v[12:13], off
	v_mad_u64_u32 v[10:11], s[14:15], v3, s9, v[8:9]
	v_add_u32_e32 v3, s12, v95
	v_max_i32_e32 v3, 0, v3
	v_cmp_lt_i32_e32 vcc, 7, v97
	v_mad_u64_u32 v[8:9], s[14:15], v3, s9, v[8:9]
	s_nop 0
	v_cndmask_b32_e64 v3, 32, -8, vcc
	v_add_u32_e32 v94, v3, v97
	v_cndmask_b32_e64 v3, 12, 13, vcc
	v_cmp_gt_u32_e32 vcc, 40, v94
	v_add_u32_e32 v3, v3, v95
	v_lshlrev_b32_e32 v89, 3, v94
	v_cndmask_b32_e32 v0, v0, v14, vcc
	v_cmp_gt_i32_e32 vcc, 24, v94
	global_load_dwordx4 v[32:35], v[10:11], off
	global_load_dwordx4 v[24:27], v[8:9], off
	v_cndmask_b32_e32 v0, v0, v15, vcc
	v_add_u32_e32 v8, v0, v89
	v_add_u32_e32 v0, s23, v3
	v_ashrrev_i32_e32 v9, 31, v8
	v_max_i32_e32 v12, -1, v0
	v_lshl_add_u64 v[8:9], v[8:9], 1, s[24:25]
	v_max_i32_e32 v10, 0, v0
	v_add_u32_e32 v12, 1, v12
	v_max_i32_e32 v0, -2, v0
	v_mad_u64_u32 v[10:11], s[14:15], v10, s9, v[8:9]
	v_mad_u64_u32 v[12:13], s[14:15], v12, s9, v[8:9]
	v_add_u32_e32 v0, 2, v0
	global_load_dwordx4 v[20:23], v[10:11], off
	s_nop 0
	global_load_dwordx4 v[12:15], v[12:13], off
	v_mad_u64_u32 v[10:11], s[14:15], v0, s9, v[8:9]
	v_add_u32_e32 v0, s12, v3
	v_max_i32_e32 v0, 0, v0
	v_mad_u64_u32 v[8:9], s[14:15], v0, s9, v[8:9]
	global_load_dwordx4 v[16:19], v[10:11], off
	s_nop 0
	global_load_dwordx4 v[8:11], v[8:9], off
	v_mov_b32_e32 v112, v198
	v_cmp_lt_i32_e64 s[50:51], 23, v88
	v_ashrrev_i32_e32 v0, 6, v112
	v_cmp_lt_i32_e64 s[48:49], 23, v108
	v_cmp_lt_i32_e64 s[46:47], 23, v105
	v_cmp_lt_i32_e64 s[44:45], 23, v97
	v_cmp_lt_i32_e64 s[42:43], 23, v94
	v_cmp_gt_i32_e32 vcc, 3, v0
	s_and_saveexec_b64 s[52:53], vcc
	s_cbranch_execz .LBB0_644
; #define LAS __attribute__((address_space(3)))
; __device__ __forceinline__ int tidx() { int t = threadIdx.x; asm volatile("" : "+v"(t)); return t; }
; __device__ __forceinline__ float softplusf_(float x) { return x > 20.f ? x : log1pf(expf(x)); }
; __device__ __forceinline__ void m2_dt(KP& P_, int l, int bc, int grp, LAS float* dtl, LAS float* acs, LAS float* wl, bool write_dec) {
;     const int tid = tidx(), wid = tid >> 6, lane = tid & 63;
;     if (wid < 3) {
;         const int head = grp * 3 + wid; const float draw = ((const float*)(p.ws + WS_DT))[((size_t)bc * 64 + lane) * 8 + head];
;         const float dt = draw < -1e29f ? 0.f : softplusf_(draw + p.in[7][l * 6 + head]);
;         const float a = -expf(p.in[8][l * 6 + head]); float x = dt * a;
	v_mad_u64_u32 v[90:91], s[14:15], s63, 3, v[0:1]
	s_load_dwordx2 s[78:79], s[20:21], 0x38
	s_load_dwordx2 s[74:75], s[20:21], 0x40
	v_mad_u64_u32 v[160:161], s[14:15], s58, 6, v[90:91]
	v_ashrrev_i32_e32 v161, 31, v160
	s_waitcnt lgkmcnt(0)
	v_lshl_add_u64 v[162:163], v[160:161], 2, s[78:79]
	v_lshl_add_u64 v[164:165], v[160:161], 2, s[74:75]
	global_load_dword v166, v[162:163], off
	global_load_dword v167, v[164:165], off
	s_ashr_i32 s23, s22, 31
	s_lshl_b64 s[14:15], s[22:23], 11
	v_and_b32_e32 v111, 63, v112
	s_add_u32 s14, s24, s14
	s_addc_u32 s15, s25, s15
	v_lshlrev_b32_e32 v0, 5, v111
	v_ashrrev_i32_e32 v91, 31, v90
	v_lshl_add_u64 v[92:93], s[14:15], 0, v[0:1]
	v_lshl_add_u64 v[92:93], v[90:91], 2, v[92:93]
	v_add_co_u32_e32 v92, vcc, 0xe9fb000, v92
	s_mov_b32 s12, 0xefa18f08
	s_nop 0
	v_addc_co_u32_e32 v93, vcc, 0, v93, vcc
	global_load_dword v113, v[92:93], off offset:2048
	s_waitcnt vmcnt(0)
	v_cmp_ngt_f32_e32 vcc, s12, v113
	s_and_saveexec_b64 s[14:15], vcc
	s_xor_b64 s[54:55], exec, s[14:15]
	s_cbranch_execz .LBB0_640
	s_load_dwordx2 s[14:15], s[20:21], 0x38
	v_mad_u64_u32 v[92:93], s[56:57], s58, 6, v[90:91]
	v_ashrrev_i32_e32 v93, 31, v92
	s_mov_b32 s12, 0x41a00000
	s_waitcnt lgkmcnt(0)
	v_lshl_add_u64 v[114:115], v[92:93], 2, s[14:15]
	v_mov_b32_e32 v0, v166
	s_waitcnt vmcnt(0)
	v_add_f32_e32 v0, v113, v0
	v_cmp_nlt_f32_e32 vcc, s12, v0
	s_and_saveexec_b64 s[56:57], vcc
	s_cbranch_execz .LBB0_639
	v_mul_f32_e32 v113, 0x3fb8aa3b, v0
	v_rndne_f32_e32 v114, v113
	v_sub_f32_e32 v115, v113, v114
	v_fma_f32 v113, v0, s17, -v113
	v_fmac_f32_e32 v113, 0x32a5705f, v0
	v_add_f32_e32 v113, v115, v113
	v_cvt_i32_f32_e32 v114, v114
	v_exp_f32_e32 v113, v113
	v_cmp_ngt_f32_e32 vcc, s93, v0
	s_mov_b32 s12, 0x3f2aaaab
	v_ldexp_f32 v113, v113, v114
	v_cndmask_b32_e32 v113, 0, v113, vcc
	v_cmp_nlt_f32_e32 vcc, s5, v0
	s_nop 1
	v_cndmask_b32_e32 v0, v213, v113, vcc
	v_add_f32_e32 v113, 1.0, v0
	v_add_f32_e32 v114, -1.0, v113
	v_sub_f32_e32 v115, v114, v113
	v_add_f32_e32 v115, 1.0, v115
	v_sub_f32_e32 v114, v0, v114
	v_add_f32_e32 v116, v114, v115
	v_frexp_mant_f32_e32 v117, v113
	v_cvt_f64_f32_e32 v[114:115], v113
	v_frexp_exp_i32_f64_e32 v114, v[114:115]
	v_cmp_gt_f32_e32 vcc, s12, v117
	s_mov_b32 s12, 0x3f317218
	s_nop 0
	v_subbrev_co_u32_e32 v122, vcc, 0, v114, vcc
	v_sub_u32_e32 v114, 0, v122
	v_ldexp_f32 v113, v113, v114
	v_ldexp_f32 v114, v116, v114
	v_add_f32_e32 v116, -1.0, v113
	v_add_f32_e32 v115, 1.0, v116
	v_sub_f32_e32 v115, v113, v115
	v_add_f32_e32 v117, v114, v115
	v_add_f32_e32 v115, 1.0, v113
	v_add_f32_e32 v118, -1.0, v115
	v_sub_f32_e32 v113, v113, v118
	v_add_f32_e32 v113, v114, v113
	v_add_f32_e32 v123, v115, v113
	v_rcp_f32_e32 v124, v123
	v_sub_f32_e32 v114, v115, v123
	v_add_f32_e32 v115, v116, v117
	v_add_f32_e32 v113, v113, v114
	v_mul_f32_e32 v126, v115, v124
	v_sub_f32_e32 v114, v116, v115
	v_mul_f32_e32 v116, v123, v126
	v_fma_f32 v118, v126, v123, -v116
	v_fmac_f32_e32 v118, v126, v113
	v_add_f32_e32 v125, v117, v114
	v_add_f32_e32 v114, v116, v118
	v_sub_f32_e32 v117, v115, v114
	v_pk_add_f32 v[120:121], v[114:115], v[116:117] neg_lo:[0,1] neg_hi:[0,1]
	v_mov_b32_e32 v119, v114
	v_pk_add_f32 v[114:115], v[120:121], v[118:119] neg_lo:[0,1] neg_hi:[0,1]
	s_nop 0
	v_add_f32_e32 v115, v125, v115
	v_add_f32_e32 v114, v114, v115
	v_add_f32_e32 v115, v117, v114
	v_mul_f32_e32 v125, v124, v115
	v_mul_f32_e32 v116, v123, v125
	v_fma_f32 v118, v125, v123, -v116
	v_fmac_f32_e32 v118, v125, v113
	v_sub_f32_e32 v113, v117, v115
	v_add_f32_e32 v113, v114, v113
	v_add_f32_e32 v114, v116, v118
	v_sub_f32_e32 v117, v115, v114
	v_pk_add_f32 v[120:121], v[114:115], v[116:117] neg_lo:[0,1] neg_hi:[0,1]
	v_mov_b32_e32 v119, v114
	v_pk_add_f32 v[114:115], v[120:121], v[118:119] neg_lo:[0,1] neg_hi:[0,1]
	s_nop 0
	v_add_f32_e32 v113, v113, v115
	v_add_f32_e32 v113, v114, v113
	v_add_f32_e32 v115, v126, v125
	v_add_f32_e32 v113, v117, v113
	v_sub_f32_e32 v114, v115, v126
	v_mul_f32_e32 v113, v124, v113
	v_sub_f32_e32 v114, v125, v114
	v_add_f32_e32 v113, v114, v113
	v_add_f32_e32 v116, v115, v113
	v_mul_f32_e32 v118, v116, v116
	v_mov_b32_e32 v114, 0x3ecc95a3
	v_fmamk_f32 v114, v118, 0x3e9b6dac, v114
	v_fmaak_f32 v179, v118, v114, 0x3f2aaada
	v_cvt_f32_i32_e32 v114, v122
	v_sub_f32_e32 v115, v116, v115
	v_sub_f32_e32 v113, v113, v115
	v_mul_f32_e32 v115, v116, v118
	v_pk_mul_f32 v[118:119], v[114:115], v[178:179]
	v_ldexp_f32 v117, v116, 1
	v_fma_f32 v116, v114, s12, -v118
	v_fmac_f32_e32 v116, 0xb102e308, v114
	v_pk_add_f32 v[114:115], v[118:119], v[116:117]
	v_ldexp_f32 v113, v113, 1
	v_sub_f32_e32 v117, v115, v117
	v_sub_f32_e32 v117, v119, v117
	v_add_f32_e32 v121, v113, v117
	v_mov_b32_e32 v120, v118
	v_pk_add_f32 v[118:119], v[114:115], v[118:119] neg_lo:[0,1] neg_hi:[0,1]
	v_pk_add_f32 v[122:123], v[114:115], v[120:121]
	v_mov_b32_e32 v117, v114
	v_mov_b32_e32 v119, v123
	v_pk_add_f32 v[124:125], v[116:117], v[118:119] neg_lo:[0,1] neg_hi:[0,1]
	v_pk_add_f32 v[116:117], v[116:117], v[118:119]
	v_mov_b32_e32 v120, v121
	v_pk_add_f32 v[118:119], v[116:117], v[114:115] op_sel:[1,0] op_sel_hi:[0,1] neg_lo:[0,1] neg_hi:[0,1]
	v_pk_add_f32 v[126:127], v[122:123], v[118:119] op_sel_hi:[1,0] neg_lo:[0,1] neg_hi:[0,1]
	v_mov_b32_e32 v122, v123
	v_mov_b32_e32 v123, v117
	v_pk_mov_b32 v[118:119], v[114:115], v[118:119] op_sel:[1,0]
	v_mov_b32_e32 v121, v114
	v_pk_add_f32 v[118:119], v[122:123], v[118:119] neg_lo:[0,1] neg_hi:[0,1]
	v_mov_b32_e32 v126, v124
	v_pk_add_f32 v[114:115], v[120:121], v[118:119] neg_lo:[0,1] neg_hi:[0,1]
	v_mov_b32_e32 v125, v117
	v_pk_add_f32 v[118:119], v[126:127], v[114:115]
	s_mov_b32 s12, 0x7f800000
	v_pk_add_f32 v[120:121], v[118:119], v[118:119] op_sel:[0,1] op_sel_hi:[1,0]
	v_cmp_neq_f32_e32 vcc, s12, v0
	v_pk_add_f32 v[116:117], v[116:117], v[120:121] op_sel:[1,0] op_sel_hi:[0,1]
	v_mov_b32_e32 v119, v116
	v_pk_add_f32 v[122:123], v[118:119], v[124:125] neg_lo:[0,1] neg_hi:[0,1]
	v_mov_b32_e32 v115, v120
	v_sub_f32_e32 v113, v118, v122
	v_pk_add_f32 v[114:115], v[114:115], v[122:123] neg_lo:[0,1] neg_hi:[0,1]
	v_sub_f32_e32 v113, v124, v113
	v_add_f32_e32 v113, v114, v113
	v_add_f32_e32 v113, v113, v115
	v_add_f32_e32 v113, v116, v113
	s_mov_b32 s12, 0x33800000
	v_cndmask_b32_e32 v113, v213, v113, vcc
	v_cmp_lt_f32_e64 vcc, |v0|, s12
	s_nop 1
	v_cndmask_b32_e32 v0, v113, v0, vcc

; __device__ __forceinline__ float softplusf_(float x) { return x > 20.f ? x : log1pf(expf(x)); }
; __device__ __forceinline__ void m2_dt(KP& P_, int l, int bc, int grp, LAS float* dtl, LAS float* acs, LAS float* wl, bool write_dec) {
;     ...
;         const float dt = draw < -1e29f ? 0.f : softplusf_(draw + p.in[7][l * 6 + head]);
;         const float a = -expf(p.in[8][l * 6 + head]); float x = dt * a;
; #pragma unroll
;         for (int off = 1; off < 64; off <<= 1) { const float v = __shfl_up(x, off); if (lane >= off) x += v; }
;         const float tot = __shfl(x, 63);
;         dtl[wid * 64 + lane] = dt; acs[wid * 64 + lane] = x; wl[wid * 64 + lane] = dt * __expf(tot - x);
;         if (write_dec && lane == 63) ((float*)(p.ws + WS_DECM))[(size_t)bc * 6 + head] = __expf(tot);
.LBB0_640:
	s_andn2_saveexec_b64 s[14:15], s[54:55]
	v_mad_u64_u32 v[92:93], s[54:55], s58, 6, v[90:91]
	v_ashrrev_i32_e32 v93, 31, v92
	v_mov_b32_e32 v0, 0
	s_or_b64 exec, exec, s[14:15]
	s_load_dwordx2 s[14:15], s[20:21], 0x40
	v_lshl_add_u32 v112, v112, 2, 0
	s_waitcnt lgkmcnt(0)
	v_lshl_add_u64 v[92:93], v[92:93], 2, s[14:15]
	v_mov_b32_e32 v92, v167
	s_waitcnt vmcnt(0)
	v_mul_f32_e32 v93, 0x3fb8aa3b, v92
	v_fma_f32 v113, v92, s17, -v93
	v_rndne_f32_e32 v114, v93
	v_fmac_f32_e32 v113, 0x32a5705f, v92
	v_sub_f32_e32 v93, v93, v114
	v_add_f32_e32 v93, v93, v113
	v_exp_f32_e32 v93, v93
	v_cvt_i32_f32_e32 v113, v114
	v_cmp_ngt_f32_e32 vcc, s93, v92
	v_ldexp_f32 v93, v93, v113
	s_nop 0
	v_cndmask_b32_e32 v93, 0, v93, vcc
	v_cmp_nlt_f32_e32 vcc, s5, v92
	v_add_u32_e32 v113, -1, v204
	s_nop 0
	v_cndmask_b32_e32 v92, v213, v93, vcc
	v_cmp_lt_i32_e32 vcc, v113, v205
	v_mul_f32_e64 v93, v0, -v92
	s_nop 0
	v_cndmask_b32_e32 v113, v113, v204, vcc
	v_lshlrev_b32_e32 v113, 2, v113
	ds_bpermute_b32 v113, v113, v93
	v_cmp_eq_u32_e32 vcc, 0, v111
	s_waitcnt lgkmcnt(0)
	v_fma_f32 v92, v0, -v92, v113
	v_cndmask_b32_e32 v92, v92, v93, vcc
	v_add_u32_e32 v93, -2, v204
	v_cmp_lt_i32_e32 vcc, v93, v205
	s_nop 1
	v_cndmask_b32_e32 v93, v93, v204, vcc
	v_lshlrev_b32_e32 v93, 2, v93
	ds_bpermute_b32 v93, v93, v92
	v_cmp_gt_u32_e32 vcc, 2, v111
	s_waitcnt lgkmcnt(0)
	v_add_f32_e32 v93, v92, v93
	v_cndmask_b32_e32 v92, v93, v92, vcc
	v_add_u32_e32 v93, -4, v204
	v_cmp_lt_i32_e32 vcc, v93, v205
	s_nop 1
	v_cndmask_b32_e32 v93, v93, v204, vcc
	v_lshlrev_b32_e32 v93, 2, v93
	ds_bpermute_b32 v93, v93, v92
	v_cmp_gt_u32_e32 vcc, 4, v111
	s_waitcnt lgkmcnt(0)
	v_add_f32_e32 v93, v92, v93
	v_cndmask_b32_e32 v92, v93, v92, vcc
	v_add_u32_e32 v93, -8, v204
	v_cmp_lt_i32_e32 vcc, v93, v205
	s_nop 1
	v_cndmask_b32_e32 v93, v93, v204, vcc
	v_lshlrev_b32_e32 v93, 2, v93
	ds_bpermute_b32 v93, v93, v92
	v_cmp_gt_u32_e32 vcc, 8, v111
	s_waitcnt lgkmcnt(0)
	v_add_f32_e32 v93, v92, v93
	v_cndmask_b32_e32 v92, v93, v92, vcc
	v_add_u32_e32 v93, -16, v204
	v_cmp_lt_i32_e32 vcc, v93, v205
	s_nop 1
	v_cndmask_b32_e32 v93, v93, v204, vcc
	v_lshlrev_b32_e32 v93, 2, v93
	ds_bpermute_b32 v93, v93, v92
	v_cmp_gt_u32_e32 vcc, 16, v111
	s_waitcnt lgkmcnt(0)
	v_add_f32_e32 v93, v92, v93
	v_cndmask_b32_e32 v92, v93, v92, vcc
	v_subrev_u32_e32 v93, 32, v204
	v_cmp_lt_i32_e32 vcc, v93, v205
	s_nop 1
	v_cndmask_b32_e32 v93, v93, v204, vcc
	v_lshlrev_b32_e32 v93, 2, v93
	ds_bpermute_b32 v93, v93, v92
	v_cmp_gt_u32_e32 vcc, 32, v111
	s_waitcnt lgkmcnt(0)
	v_add_f32_e32 v93, v92, v93
	v_cndmask_b32_e32 v93, v93, v92, vcc
	v_lshl_or_b32 v92, v204, 2, v214
	ds_bpermute_b32 v92, v92, v93
	ds_write2st64_b32 v112, v0, v93 offset0:180 offset1:183
	v_cmp_eq_u32_e32 vcc, 63, v111
	s_waitcnt lgkmcnt(1)
	v_sub_f32_e32 v93, v92, v93
	v_mul_f32_e32 v93, 0x3fb8aa3b, v93
	v_exp_f32_e32 v93, v93
	s_nop 0
	v_mul_f32_e32 v0, v0, v93
	ds_write_b32 v112, v0 offset:47616
	s_and_b64 exec, exec, vcc
	s_cbranch_execz .LBB0_644
	s_mul_i32 s14, s22, 24
	v_mul_f32_e32 v0, 0x3fb8aa3b, v92
	s_mul_hi_i32 s12, s22, 24
	s_add_u32 s14, s24, s14
	v_exp_f32_e32 v0, v0
	s_addc_u32 s15, s25, s12
	v_lshl_add_u64 v[90:91], v[90:91], 2, s[14:15]
	v_add_co_u32_e32 v90, vcc, 0xe9f9000, v90
	s_nop 1
	v_addc_co_u32_e32 v91, vcc, 0, v91, vcc
	global_store_dword v[90:91], v0, off offset:2048

; __device__ __forceinline__ unsigned xb_ld(unsigned* q)              { return __hip_atomic_load(q, __ATOMIC_RELAXED, __HIP_MEMORY_SCOPE_AGENT); }
; __device__ __forceinline__ void xcd_barrier_complete(unsigned* bar, unsigned x, unsigned& nloc, unsigned& nx) {
;     ...
;     for (;;) {
;         sum = 0u; cnt = 0u; mine = 0u;
; #pragma unroll
;         for (unsigned j = 0; j < 16; ++j) { const unsigned c = xb_ld(&bar[XB_XCNT(j)]); sum += c; cnt += (c > 0u) ? 1u : 0u; mine = (j == x) ? c : mine; }
;         if (sum == G) break;
.LBB0_1084:
	v_readlane_b32 s12, v253, 57
	v_readlane_b32 s13, v253, 58
	s_mov_b64 s[18:19], -1
	s_nop 4
	global_load_dword v0, v1, s[12:13] sc1
	v_readlane_b32 s12, v253, 59
	v_readlane_b32 s13, v253, 60
	s_nop 4
	global_load_dword v2, v1, s[12:13] sc1
	v_readlane_b32 s12, v253, 61
	v_readlane_b32 s13, v253, 62
	s_nop 4
	global_load_dword v3, v1, s[12:13] sc1
	v_readlane_b32 s12, v253, 63
	v_readlane_b32 s13, v254, 0
	s_nop 4
	global_load_dword v8, v1, s[12:13] sc1
	v_readlane_b32 s12, v254, 1
	v_readlane_b32 s13, v254, 2
	s_nop 4
	global_load_dword v9, v1, s[12:13] sc1
	v_readlane_b32 s12, v254, 3
	v_readlane_b32 s13, v254, 4
	s_nop 4
	global_load_dword v10, v1, s[12:13] sc1
	v_readlane_b32 s12, v254, 5
	v_readlane_b32 s13, v254, 6
	s_nop 4
	global_load_dword v11, v1, s[12:13] sc1
	v_readlane_b32 s12, v254, 7
	v_readlane_b32 s13, v254, 8
	s_nop 4
	global_load_dword v12, v1, s[12:13] sc1
	v_readlane_b32 s12, v254, 9
	v_readlane_b32 s13, v254, 10
	s_nop 4
	global_load_dword v13, v1, s[12:13] sc1
	v_readlane_b32 s12, v254, 11
	v_readlane_b32 s13, v254, 12
	s_nop 4
	global_load_dword v14, v1, s[12:13] sc1
	v_readlane_b32 s12, v254, 13
	v_readlane_b32 s13, v254, 14
	s_nop 4
	global_load_dword v15, v1, s[12:13] sc1
	v_readlane_b32 s12, v254, 15
	v_readlane_b32 s13, v254, 16
	s_nop 4
	global_load_dword v16, v1, s[12:13] sc1
	v_readlane_b32 s12, v254, 17
	v_readlane_b32 s13, v254, 18
	s_nop 4
	global_load_dword v17, v1, s[12:13] sc1
	v_readlane_b32 s12, v254, 19
	v_readlane_b32 s13, v254, 20
	s_nop 4
	global_load_dword v18, v1, s[12:13] sc1
	v_readlane_b32 s12, v254, 21
	v_readlane_b32 s13, v254, 22
	s_nop 4
	global_load_dword v19, v1, s[12:13] sc1
	v_readlane_b32 s12, v254, 23
	v_readlane_b32 s13, v254, 24
	s_nop 4
	global_load_dword v20, v1, s[12:13] sc1
	s_mov_b64 s[12:13], -1
	s_waitcnt vmcnt(0)
	v_add_u32_e32 v21, v2, v0
	v_add_u32_e32 v21, v21, v3
	v_add_u32_e32 v21, v21, v8
	v_add_u32_e32 v21, v21, v9
	v_add_u32_e32 v21, v21, v10
	v_add_u32_e32 v21, v21, v11
	v_add_u32_e32 v21, v21, v12
	v_add_u32_e32 v21, v21, v13
	v_add_u32_e32 v21, v21, v14
	v_add_u32_e32 v21, v21, v15
	v_add_u32_e32 v21, v21, v16
	v_add_u32_e32 v21, v21, v17
	v_add_u32_e32 v21, v21, v18
	v_add_u32_e32 v21, v21, v19
	v_add_u32_e32 v21, v21, v20
	v_cmp_eq_u32_e32 vcc, s20, v21
	s_cbranch_vccnz .LBB0_1083
	s_and_b32 s12, s21, 0xff
	s_cmp_eq_u32 s12, 0
	s_mov_b64 s[12:13], -1
	s_mov_b64 s[14:15], -1
	s_sleep 1
	s_cbranch_scc1 .LBB0_1088
	s_and_b64 vcc, exec, s[14:15]
	s_cbranch_vccz .LBB0_1083
